# P4 ukv GEMM: waves 4-7 take column quarter wc^2 so each SIMD has one K-side and one V^T-side wave in the epilogue (was two V^T-side waves on two SIMDs)
# speedup vs baseline: 1.0027x; 1.0027x over previous
; #define PG8_STAGE(bufoff, gbase, voff) do { _Pragma("unroll") for (int _i = 0; _i < 2; ++_i) \
;         __builtin_amdgcn_global_load_lds((const unsigned*)((const char*)(gbase) + (voff)[_i]), (PG8_LAS unsigned*)(lds + (bufoff) + ldsw + _i * 8192), 16, 0, 0); } while (0)
; #define PG8_WAIT_V(n) asm volatile("s_waitcnt vmcnt(" #n ")" ::: "memory")
; #define PG8_BAR __builtin_amdgcn_s_barrier()
; template <class Epi, class Sched, bool ALIGN_EPI = false, bool SP2 = false>
; __device__ __forceinline__ void gemm_phase(PG8_LAS unsigned char* lds, const Gemm g, const Sched& S, const Epi& E) {
;     const int tid = threadIdx.x, wid = __builtin_amdgcn_readfirstlane(tid >> 6), lane = tid & 63, wr = wid >> 2, wc = wid & 3, fr = lane & 15, fq = lane >> 4;
;     const int K = g.K, nt = K / BK;
;     unsigned voffA[2], voffB[2];
; #pragma unroll
;     for (int i = 0; i < 2; ++i) { int R, C; stage_rc(tid * 16 + i * 8192, R, C); const int Rb = Epi::PERM ? ((R & ~31) + perm32(R & 31)) : R;
;         voffA[i] = (unsigned)(R * K + C) * 2u; voffB[i] = (unsigned)(Rb * K + C) * 2u; }
;     const size_t kstep = (size_t)(BK * 2);
;     const size_t hstep = (size_t)HALF * K * 2;
;     const size_t tstep = 2 * hstep;
;     const unsigned ldsw = (unsigned)wid * 1024u;
;     const int aoff = lds_byte(wr * 64 + fr, fq * 8), boff = lds_byte(wc * 32 + fr, fq * 8);
;     ...
;         PG8_STAGE(PG8_SB(1, 0), cB + kstep, voffB); PG8_STAGE(PG8_SA(1, 0), cA + kstep, voffA); PG8_STAGE(PG8_SB(1, 1), cB + hstep + kstep, voffB);
;         PG8_WAIT_V(6); PG8_BAR;
.LBB0_1214:
	s_add_u32 s18, s6, 0x3b00000
	s_addc_u32 s19, s7, 0
	s_add_u32 s20, s6, 0xe700000
	s_addc_u32 s21, s7, 0
	s_add_u32 s22, s6, 0xd700000
	s_mov_b64 s[24:25], 0x80
	s_addc_u32 s23, s7, 0
	s_add_i32 m0, s44, 0x18000
	v_lshl_add_u64 v[8:9], v[8:9], 0, s[24:25]
	s_waitcnt vmcnt(2)
	s_barrier
	global_load_lds_dwordx4 v[8:9], off
	v_lshl_add_u64 v[4:5], v[4:5], 0, s[24:25]
	s_add_i32 m0, s44, 0x1a000
	s_add_i32 s61, s44, 0x8000
	global_load_lds_dwordx4 v[4:5], off
	v_lshl_add_u64 v[4:5], v[6:7], 0, s[24:25]
	s_mov_b32 m0, s61
	s_add_i32 s66, s44, 0xa000
	global_load_lds_dwordx4 v[4:5], off
	v_lshl_add_u64 v[4:5], v[10:11], 0, s[24:25]
	s_mov_b32 m0, s66
	v_lshl_add_u64 v[2:3], v[2:3], 0, s[24:25]
	global_load_lds_dwordx4 v[4:5], off
	s_add_i32 m0, s44, 0x1c000
	v_lshl_add_u64 v[0:1], v[0:1], 0, s[24:25]
	global_load_lds_dwordx4 v[2:3], off
	s_add_i32 m0, s44, 0x1e000
	s_lshr_b32 s3, s3, 26
	global_load_lds_dwordx4 v[0:1], off
	s_add_i32 s3, s2, s3
	v_lshlrev_b32_e32 v2, 2, v129
	s_and_b32 s4, s4, 3
	s_lshl_b32 s100, s5, 1
	s_xor_b32 s4, s4, s100
	s_nop 0
	s_nop 0
	s_nop 0
	s_nop 0
	s_nop 0
	s_nop 0
	s_ashr_i32 s67, s3, 6
	v_lshl_or_b32 v1, v129, 6, v143
	s_lshl_b32 s3, s5, 13
	v_and_b32_e32 v2, 32, v2
	v_or_b32_e32 v0, v143, v163
	v_bitop3_b32 v1, v1, s3, v2 bitop3:0xde
	s_lshl_b32 s3, s4, 12
	v_bitop3_b32 v162, s3, v0, v162 bitop3:0xf6
	v_lshlrev_b32_e32 v0, 16, v161
	v_lshl_or_b32 v0, s4, 18, v0
	v_add_u32_e32 v163, 0xfff80000, v0
	v_add_u32_e32 v0, v159, v158
	s_lshl_b32 s68, s5, 6
	s_lshl_b32 s69, s4, 5
	v_mul_lo_u32 v0, s2, v0
	s_cmp_gt_i32 s2, 63
	v_lshlrev_b32_e32 v0, 1, v0
	s_cselect_b64 s[26:27], -1, 0
	s_add_i32 s70, s67, -2
	v_add3_u32 v140, v156, v0, v157
	v_add_u32_e32 v0, v131, v158
	s_cmpk_lt_u32 s34, 0x100
	v_mul_lo_u32 v0, s2, v0
	s_waitcnt vmcnt(6)
	s_cselect_b64 s[34:35], -1, 0
	s_cmp_gt_u32 s4, 1
	v_lshlrev_b32_e32 v0, 1, v0
	s_cselect_b64 s[42:43], -1, 0
	v_lshl_add_u64 v[144:145], s[8:9], 0, v[140:141]
	v_add3_u32 v140, v156, v0, v157
	s_add_i32 s71, 0, 0x10000
	s_add_i32 s74, 0, 0x14000
	v_lshlrev_b32_e32 v142, 3, v161
	v_lshl_add_u64 v[146:147], s[8:9], 0, v[140:141]
	v_mov_b64_e32 v[148:149], 0x100
	v_mov_b64_e32 v[150:151], 0xff
	v_add_u32_e32 v164, s71, v162
	v_add_u32_e32 v165, s74, v162
	v_add_u32_e32 v166, 0, v1
	v_mov_b32_e32 v167, 0x358637bd
	s_movk_i32 s75, 0x1fcf
	s_movk_i32 s76, 0x7fff
	s_movk_i32 s77, 0x1fdf
	s_movk_i32 s78, 0x1fef
	s_movk_i32 s79, 0x1fff
	s_mov_b32 s80, 0
	s_barrier
	s_branch .LBB0_1217
